# o5 + weight-conversion filler items run by idle workgroups in the w_in GEMM's last round (4 per WG), separate filler counter
# speedup vs baseline: 1.0129x; 1.0050x over previous
_Z5k_fwd1P:
	s_load_dwordx8 s[80:87], s[0:1], 0xc0
	s_mov_b32 s98, 0
	s_mov_b32 s99, 0
	s_mov_b32 s100, 0
	v_cmp_gt_u32_e32 vcc, 4, v0
	v_writelane_b32 v253, s2, 0
	s_and_saveexec_b64 s[2:3], vcc
	v_lshl_add_u32 v1, v0, 2, 0
	v_add_u32_e32 v1, 0x27000, v1
	v_mov_b32_e32 v2, 0
	ds_write_b32 v1, v2
	s_or_b64 exec, exec, s[2:3]
	s_load_dwordx16 s[4:19], s[0:1], 0x40
	s_waitcnt lgkmcnt(0)
	s_barrier
	s_getreg_b32 s2, hwreg(HW_REG_XCC_ID, 0, 4)
	v_writelane_b32 v253, s4, 1
	s_and_b32 s2, s2, 15
	s_nop 0
	v_writelane_b32 v253, s5, 2
	v_writelane_b32 v253, s6, 3
	v_writelane_b32 v253, s7, 4
	v_writelane_b32 v253, s8, 5
	v_writelane_b32 v253, s9, 6
	v_writelane_b32 v253, s10, 7
	v_writelane_b32 v253, s11, 8
	v_writelane_b32 v253, s12, 9
	v_writelane_b32 v253, s13, 10
	v_writelane_b32 v253, s14, 11
	v_writelane_b32 v253, s15, 12
	v_writelane_b32 v253, s16, 13
	v_writelane_b32 v253, s17, 14
	v_writelane_b32 v253, s18, 15
	v_writelane_b32 v253, s19, 16
	v_writelane_b32 v253, s2, 17
	v_cmp_eq_u32_e64 s[4:5], 0, v0
	s_mov_b64 s[2:3], exec
	s_nop 0
	v_writelane_b32 v253, s4, 18
	s_nop 1
	v_writelane_b32 v253, s5, 19
	s_and_b64 s[4:5], s[2:3], s[4:5]
	s_mov_b64 exec, s[4:5]
	s_cbranch_execz .LBB0_5
	s_mov_b64 s[4:5], exec
	v_mbcnt_lo_u32_b32 v1, s4, 0
	v_mbcnt_hi_u32_b32 v1, s5, v1
	v_cmp_eq_u32_e32 vcc, 0, v1
	s_and_b64 s[6:7], exec, vcc
	s_mov_b64 exec, s[6:7]
	s_cbranch_execz .LBB0_5
	v_readlane_b32 s6, v253, 17
	s_lshl_b32 s6, s6, 8
	s_bcnt1_i32_b64 s4, s[4:5]
	v_mov_b32_e32 v1, s6
	v_mov_b32_e32 v2, s4
	global_atomic_add v1, v2, s[86:87] offset:1024

.LBB0_1169:
	s_waitcnt vmcnt(0)
	v_readlane_b32 s80, v254, 8
	v_readlane_b32 s81, v254, 9
	v_readlane_b32 s82, v254, 10
	v_readlane_b32 s83, v254, 11
	v_readlane_b32 s84, v254, 12
	v_readlane_b32 s85, v254, 13
	v_readlane_b32 s86, v254, 14
	v_readlane_b32 s87, v254, 15
	s_barrier
	v_readlane_b32 s101, v253, 0
	s_nop 3
	s_cmpk_lt_u32 s101, 0x61
	s_cbranch_scc1 .LBB0_1170
	s_mov_b32 s99, 1
	s_movk_i32 s98, 0x410
	s_movk_i32 s100, 0x5
	s_add_u32 s0, s86, 0xc600
	s_addc_u32 s1, s87, 0
	v_writelane_b32 v254, s0, 22
	v_mov_b32_e32 v1, v0
	s_branch .Lmix1_entry
.Lpre_return:
	s_mov_b32 s99, 0
	s_mov_b32 s98, 0
	v_mbcnt_lo_u32_b32 v202, -1, 0

.LBB0_1222:
	s_or_b64 exec, exec, s[0:1]
	s_mov_b32 s98, 0
	s_add_u32 s0, s86, 0xc200
	s_addc_u32 s1, s87, 0
	v_writelane_b32 v254, s0, 22
	s_waitcnt lgkmcnt(0)
	v_mov_b32_e32 v1, v0
	s_barrier
.Lmix1_entry:
	v_writelane_b32 v254, s1, 23
	v_mov_b32_e32 v135, 0
	v_cmp_eq_u32_e64 s[0:1], 0, v1
	v_ashrrev_i32_e32 v2, 6, v1
	v_add_u32_e32 v131, 0xffffdf80, v2
	v_writelane_b32 v254, s0, 24
	v_and_b32_e32 v2, 63, v1
	v_lshlrev_b32_e32 v3, 2, v2
	v_writelane_b32 v254, s1, 25
	v_cmp_gt_u32_e64 s[0:1], 16, v2
	v_and_b32_e32 v132, 48, v1
	v_lshlrev_b32_e32 v2, 4, v1
	v_writelane_b32 v254, s0, 26
	v_and_b32_e32 v130, 60, v3
	v_and_b32_e32 v2, 16, v2
	v_writelane_b32 v254, s1, 27
	v_readlane_b32 s0, v253, 40
	v_readlane_b32 s1, v253, 41
	s_add_u32 s0, s86, 0x8c60200
	s_addc_u32 s1, s87, 0
	v_writelane_b32 v254, s0, 28
	v_readlane_b32 s6, v253, 46
	v_readlane_b32 s7, v253, 47
	v_writelane_b32 v254, s1, 29
	s_add_u32 s0, s86, 0xb860200
	s_addc_u32 s1, s87, 0
	v_writelane_b32 v254, s0, 30
	s_cmp_lg_u64 s[6:7], 0
	v_lshlrev_b32_e32 v134, 2, v132
	v_readlane_b32 s8, v253, 48
	v_readlane_b32 s9, v253, 49
	v_writelane_b32 v254, s1, 31
	s_cselect_b64 s[0:1], -1, 0
	v_and_or_b32 v2, v3, 32, v2
	v_lshlrev_b32_e32 v1, 1, v1
	v_lshl_add_u64 v[136:137], s[6:7], 0, v[134:135]
	v_lshl_add_u64 v[138:139], s[8:9], 0, v[134:135]
	v_writelane_b32 v254, s0, 32
	v_lshlrev_b32_e32 v134, 2, v130
	v_and_or_b32 v133, v1, 12, v2
	v_writelane_b32 v254, s1, 33
	v_lshl_add_u64 v[2:3], s[86:87], 0, v[134:135]
	s_mov_b64 s[0:1], 0x60000
	v_lshl_add_u64 v[140:141], v[2:3], 0, s[0:1]
	s_mov_b64 s[0:1], 0x54000
	v_lshl_add_u64 v[142:143], v[2:3], 0, s[0:1]
	s_add_u32 s0, s86, 0x8460200
	s_addc_u32 s1, s87, 0
	v_writelane_b32 v254, s0, 34
	s_mov_b32 s49, 0
	v_mov_b32_e32 v154, 0x260
	v_writelane_b32 v254, s1, 35
	s_add_u32 s0, s86, 0x23228200
	v_writelane_b32 v254, s0, 36
	s_addc_u32 s0, s87, 0
	v_writelane_b32 v254, s0, 37
	s_add_u32 s0, s86, 0x23230200
	v_writelane_b32 v254, s0, 38
	s_addc_u32 s0, s87, 0
	v_writelane_b32 v254, s0, 39
	s_add_u32 s0, s86, 0x39ebc200
	s_addc_u32 s1, s87, 0
	v_writelane_b32 v254, s0, 40
	s_movk_i32 s50, 0x1ff
	s_movk_i32 s57, 0x240
	v_writelane_b32 v254, s1, 41
	s_add_u32 s0, s84, 0x6660000
	v_writelane_b32 v254, s0, 42
	s_addc_u32 s0, s85, 0
	v_writelane_b32 v254, s0, 43
	s_add_u32 s0, s86, 0x233bc200
	s_addc_u32 s1, s87, 0
	s_add_u32 s78, s86, 0x232b4200
	s_addc_u32 s79, s87, 0
	s_add_u32 s54, s86, 0x23338200
	v_writelane_b32 v254, s0, 16
	s_addc_u32 s55, s87, 0
	v_lshlrev_b32_e32 v144, 2, v130
	v_writelane_b32 v254, s1, 17
	s_add_u32 s0, s86, 0x8000
	s_addc_u32 s1, s87, 0
	v_writelane_b32 v254, s0, 44
	v_lshlrev_b32_e32 v146, 1, v132
	v_mbcnt_hi_u32_b32 v202, -1, v202
	v_writelane_b32 v254, s1, 45
	s_add_u32 s0, s86, 0x23120200
	s_addc_u32 s1, s87, 0
	v_writelane_b32 v254, s0, 46
	v_mov_b32_e32 v156, 0x50a
	v_mov_b32_e32 v157, 0x1a00
	v_writelane_b32 v254, s1, 47
	s_add_u32 s0, s86, 0x35cbc200
	s_addc_u32 s1, s87, 0
	s_add_u32 s76, s86, 0x39cbc200
	v_writelane_b32 v254, s0, 48
	s_addc_u32 s77, s87, 0
	v_mov_b32_e32 v158, 0x5e00
	v_writelane_b32 v254, s1, 49
	s_add_u32 s0, s86, 0x220a0200
	s_addc_u32 s1, s87, 0
	v_writelane_b32 v254, s0, 50
	s_add_i32 s56, 0, 0x13200
	v_mov_b32_e32 v192, v135
	v_writelane_b32 v254, s1, 51
	s_add_i32 s1, 0, 0x15600
	v_writelane_b32 v254, s1, 52
	s_add_i32 s1, 0, 0x16a00
	s_add_i32 s0, 0, 0x27040
	v_writelane_b32 v254, s1, 53
	v_writelane_b32 v254, s0, 54
	v_mov_b32_e32 v155, s0
	v_mov_b32_e32 v193, v135
	v_mov_b32_e32 v159, 0xe0
	v_readlane_b32 s2, v253, 42
	v_readlane_b32 s3, v253, 43
	v_readlane_b32 s4, v253, 44
	v_readlane_b32 s5, v253, 45
	v_readlane_b32 s10, v253, 50
	v_readlane_b32 s11, v253, 51
	v_readlane_b32 s12, v253, 52
	v_readlane_b32 s13, v253, 53
	v_readlane_b32 s14, v253, 54
	v_readlane_b32 s15, v253, 55
	s_branch .LBB0_1225

.LBB0_1225:
	s_cmp_eq_u32 s99, 0
	s_cbranch_scc1 .Lq_go
	s_sub_u32 s100, s100, 1
	s_cmp_eq_u32 s100, 0
	s_cbranch_scc1 .Lpre_return

.LBB0_1229:
	s_or_b64 exec, exec, s[0:1]
	s_waitcnt lgkmcnt(0)
	s_barrier
	ds_read_b32 v1, v155
	s_movk_i32 s0, 0x8af
	s_waitcnt lgkmcnt(0)
	v_add_u32_e32 v1, s98, v1
	v_cmp_lt_u32_e32 vcc, s0, v1
	v_readfirstlane_b32 s42, v1
	s_mov_b64 s[0:1], -1
	s_cbranch_vccnz .LBB0_1224
	s_cmpk_gt_u32 s42, 0xff
	s_cbranch_scc0 .LBB0_1402
	s_cmpk_gt_u32 s42, 0x2ff
	s_cbranch_scc0 .LBB0_1300
	s_cmpk_gt_u32 s42, 0x407
	s_cbranch_scc0 .LBB0_1274
	s_cmpk_gt_u32 s42, 0x40f
	s_cbranch_scc0 .LBB0_1271
	s_cmp_lg_u32 s98, 0
	s_cbranch_scc1 .Lfill_go
	s_movk_i32 s98, 0x410
	s_add_u32 s0, s86, 0xc600
	s_addc_u32 s1, s87, 0
	v_writelane_b32 v254, s0, 22
	s_nop 0
	v_writelane_b32 v254, s1, 23
	s_branch .LBB0_1225
.Lfill_go:
	v_lshl_add_u32 v1, s42, 3, v131
	s_movk_i32 s0, 0x2500
	v_cmp_gt_i32_e32 vcc, s0, v1
	s_and_saveexec_b64 s[0:1], vcc
	s_xor_b64 s[2:3], exec, s[0:1]
	s_cbranch_execz .LBB0_1270
	s_movk_i32 s0, 0x2100
	v_lshlrev_b32_e32 v2, 6, v1
	v_cmp_gt_i32_e32 vcc, s0, v1
	s_and_saveexec_b64 s[0:1], vcc
	s_xor_b64 s[4:5], exec, s[0:1]
	s_cbranch_execz .LBB0_1267
	s_movk_i32 s0, 0x15ff
	v_cmp_lt_i32_e32 vcc, s0, v1
	s_and_saveexec_b64 s[0:1], vcc
	s_xor_b64 s[0:1], exec, s[0:1]
	s_cbranch_execz .LBB0_1238
	v_lshlrev_b32_e32 v1, 1, v1
	v_and_b32_e32 v1, 0x7fffffc0, v1
	v_add_u32_e32 v66, 0xffffd400, v1
	v_or_b32_e32 v134, v66, v132
	v_readlane_b32 s8, v253, 40
	v_and_b32_e32 v68, 0x7c0, v2
	v_lshlrev_b64 v[2:3], 13, v[134:135]
	v_readlane_b32 s22, v253, 54
	v_readlane_b32 s23, v253, 55
	v_lshlrev_b32_e32 v134, 2, v68
	v_mov_b32_e32 v145, v135
	v_lshl_add_u64 v[2:3], s[22:23], 0, v[2:3]
	v_lshl_add_u64 v[2:3], v[2:3], 0, v[134:135]
	s_waitcnt vmcnt(9)
	v_lshl_add_u64 v[58:59], v[2:3], 0, v[144:145]
	s_movk_i32 s8, 0x2000
	v_add_co_u32_e32 v6, vcc, s8, v58
	s_movk_i32 s6, 0x4000
	s_nop 0
	v_addc_co_u32_e32 v7, vcc, 0, v59, vcc
	v_add_co_u32_e32 v10, vcc, s6, v58
	s_movk_i32 s6, 0x6000
	s_nop 0
	v_addc_co_u32_e32 v11, vcc, 0, v59, vcc
	v_add_co_u32_e32 v14, vcc, s6, v58
	s_mov_b32 s6, 0x8000
	s_nop 0
	v_addc_co_u32_e32 v15, vcc, 0, v59, vcc
	v_add_co_u32_e32 v18, vcc, s6, v58
	s_mov_b32 s6, 0xa000
	s_nop 0
	v_addc_co_u32_e32 v19, vcc, 0, v59, vcc
	v_add_co_u32_e32 v22, vcc, s6, v58
	s_mov_b32 s6, 0xc000
	s_nop 0
	v_addc_co_u32_e32 v23, vcc, 0, v59, vcc
	v_add_co_u32_e32 v26, vcc, s6, v58
	s_mov_b32 s6, 0xe000
	s_nop 0
	v_addc_co_u32_e32 v27, vcc, 0, v59, vcc
	v_add_co_u32_e32 v30, vcc, s6, v58
	s_mov_b32 s6, 0x10000
	s_nop 0
	v_addc_co_u32_e32 v31, vcc, 0, v59, vcc
	v_add_co_u32_e32 v34, vcc, s6, v58
	s_mov_b32 s6, 0x12000
	s_nop 0
	v_addc_co_u32_e32 v35, vcc, 0, v59, vcc
	v_add_co_u32_e32 v38, vcc, s6, v58
	s_mov_b32 s6, 0x14000
	s_nop 0
	v_addc_co_u32_e32 v39, vcc, 0, v59, vcc
	v_add_co_u32_e32 v42, vcc, s6, v58
	s_mov_b32 s6, 0x16000
	s_nop 0
	v_addc_co_u32_e32 v43, vcc, 0, v59, vcc
	v_add_co_u32_e32 v46, vcc, s6, v58
	s_mov_b32 s6, 0x18000
	s_nop 0
	v_addc_co_u32_e32 v47, vcc, 0, v59, vcc
	v_add_co_u32_e32 v50, vcc, s6, v58
	s_mov_b32 s6, 0x1a000
	s_nop 0
	v_addc_co_u32_e32 v51, vcc, 0, v59, vcc
	v_add_co_u32_e32 v54, vcc, s6, v58
	s_mov_b32 s6, 0x1c000
	s_nop 0
	v_addc_co_u32_e32 v55, vcc, 0, v59, vcc
	v_add_co_u32_e32 v60, vcc, s6, v58
	s_mov_b32 s6, 0x1e000
	s_nop 0
	v_addc_co_u32_e32 v61, vcc, 0, v59, vcc
	s_waitcnt vmcnt(8)
	v_add_co_u32_e32 v62, vcc, s6, v58
	global_load_dwordx4 v[2:5], v[58:59], off nt
	s_nop 0
	global_load_dwordx4 v[6:9], v[6:7], off nt
	s_nop 0
	global_load_dwordx4 v[10:13], v[10:11], off nt
	s_nop 0
	global_load_dwordx4 v[14:17], v[14:15], off nt
	s_nop 0
	global_load_dwordx4 v[18:21], v[18:19], off nt
	s_nop 0
	global_load_dwordx4 v[22:25], v[22:23], off nt
	s_nop 0
	global_load_dwordx4 v[26:29], v[26:27], off nt
	s_nop 0
	global_load_dwordx4 v[30:33], v[30:31], off nt
	v_addc_co_u32_e32 v63, vcc, 0, v59, vcc
	global_load_dwordx4 v[34:37], v[34:35], off nt
	s_nop 0
	global_load_dwordx4 v[38:41], v[38:39], off nt
	s_nop 0
	global_load_dwordx4 v[42:45], v[42:43], off nt
	s_nop 0
	global_load_dwordx4 v[46:49], v[46:47], off nt
	s_nop 0
	global_load_dwordx4 v[50:53], v[50:51], off nt
	s_nop 0
	global_load_dwordx4 v[54:57], v[54:55], off nt
	s_nop 0
	global_load_dwordx4 v[58:61], v[60:61], off nt
	s_nop 0
	global_load_dwordx4 v[62:65], v[62:63], off nt
	v_or_b32_e32 v1, v68, v130
	v_mul_u32_u24_e32 v1, 0x1600, v1
	v_readlane_b32 s6, v254, 30
	v_lshlrev_b32_e32 v134, 1, v1
	v_readlane_b32 s7, v254, 31
	v_mov_b32_e32 v67, v135
	v_mov_b32_e32 v147, v135
	v_lshl_add_u64 v[68:69], s[6:7], 0, v[134:135]
	v_lshl_add_u64 v[66:67], v[66:67], 1, v[68:69]
	v_lshl_add_u64 v[74:75], v[66:67], 0, v[146:147]
	s_movk_i32 s6, 0x5000
	v_readlane_b32 s9, v253, 41
	v_readlane_b32 s10, v253, 42
	v_readlane_b32 s11, v253, 43
	v_readlane_b32 s12, v253, 44
	v_readlane_b32 s13, v253, 45
	v_readlane_b32 s14, v253, 46
	v_readlane_b32 s15, v253, 47
	v_readlane_b32 s16, v253, 48
	v_readlane_b32 s17, v253, 49
	v_readlane_b32 s18, v253, 50
	v_readlane_b32 s19, v253, 51
	v_readlane_b32 s20, v253, 52
	v_readlane_b32 s21, v253, 53
	s_waitcnt vmcnt(14)
	v_cvt_pk_bf16_f32 v66, v2, v6
	s_waitcnt vmcnt(12)
	v_cvt_pk_bf16_f32 v67, v10, v14
	s_waitcnt vmcnt(10)
	v_cvt_pk_bf16_f32 v68, v18, v22
	s_waitcnt vmcnt(8)
	v_cvt_pk_bf16_f32 v69, v26, v30
	v_add_co_u32_e32 v2, vcc, s8, v74
	s_waitcnt vmcnt(6)
	v_cvt_pk_bf16_f32 v70, v34, v38
	s_waitcnt vmcnt(4)
	v_cvt_pk_bf16_f32 v71, v42, v46
	s_waitcnt vmcnt(2)
	v_cvt_pk_bf16_f32 v72, v50, v54
	s_waitcnt vmcnt(0)
	v_cvt_pk_bf16_f32 v73, v58, v62
	global_store_dwordx4 v[74:75], v[66:69], off
	global_store_dwordx4 v[74:75], v[70:73], off offset:16
	v_cvt_pk_bf16_f32 v6, v37, v41
	v_cvt_pk_bf16_f32 v66, v3, v7
	v_cvt_pk_bf16_f32 v67, v11, v15
	v_cvt_pk_bf16_f32 v68, v19, v23
	v_cvt_pk_bf16_f32 v69, v27, v31
	v_addc_co_u32_e32 v3, vcc, 0, v75, vcc
	v_cvt_pk_bf16_f32 v70, v35, v39
	v_cvt_pk_bf16_f32 v71, v43, v47
	v_cvt_pk_bf16_f32 v72, v51, v55
	v_cvt_pk_bf16_f32 v73, v59, v63
	global_store_dwordx4 v[2:3], v[66:69], off offset:3072
	global_store_dwordx4 v[2:3], v[70:73], off offset:3088
	v_add_co_u32_e32 v2, vcc, s6, v74
	v_cvt_pk_bf16_f32 v66, v4, v8
	s_nop 0
	v_addc_co_u32_e32 v3, vcc, 0, v75, vcc
	v_cvt_pk_bf16_f32 v67, v12, v16
	v_cvt_pk_bf16_f32 v68, v20, v24
	v_cvt_pk_bf16_f32 v69, v28, v32
	v_add_co_u32_e32 v10, vcc, 0x8000, v74
	v_cvt_pk_bf16_f32 v70, v36, v40
	v_cvt_pk_bf16_f32 v71, v44, v48
	v_cvt_pk_bf16_f32 v72, v52, v56
	v_cvt_pk_bf16_f32 v73, v60, v64
	global_store_dwordx4 v[2:3], v[66:69], off offset:2048
	global_store_dwordx4 v[2:3], v[70:73], off offset:2064
	v_cvt_pk_bf16_f32 v2, v5, v9
	v_cvt_pk_bf16_f32 v3, v13, v17
	v_cvt_pk_bf16_f32 v4, v21, v25
	v_cvt_pk_bf16_f32 v5, v29, v33
	v_addc_co_u32_e32 v11, vcc, 0, v75, vcc
	v_cvt_pk_bf16_f32 v7, v45, v49
	v_cvt_pk_bf16_f32 v8, v53, v57
	v_cvt_pk_bf16_f32 v9, v61, v65
	global_store_dwordx4 v[10:11], v[2:5], off offset:1024
	global_store_dwordx4 v[10:11], v[6:9], off offset:1040

.LBB0_1487:
	s_cmp_lg_u32 s99, 0
	s_cbranch_scc1 .Lpre_return
	s_waitcnt vmcnt(0)
	s_waitcnt lgkmcnt(0)
	s_barrier
	s_mov_b64 s[0:1], exec
	v_readlane_b32 s2, v253, 18
	v_readlane_b32 s3, v253, 19
	s_and_b64 s[2:3], s[0:1], s[2:3]
	s_mov_b64 exec, s[2:3]
	s_cbranch_execz .LBB0_1539
	s_add_i32 s2, 0, 0x27000
	v_mov_b32_e32 v1, s2
	s_waitcnt vmcnt(0) expcnt(0) lgkmcnt(0)
	ds_read_b32 v3, v1
	s_add_i32 s2, 0, 0x27004
	v_mov_b32_e32 v1, s2
	ds_read_b32 v1, v1
	s_waitcnt lgkmcnt(1)
	v_cmp_ne_u32_e32 vcc, 0, v3
	s_cbranch_vccnz .LBB0_1503
	v_readlane_b32 s2, v253, 21
	v_readlane_b32 s3, v253, 22
	s_load_dwordx2 s[6:7], s[2:3], 0x4
	s_add_u32 s2, s86, 0x1000
	s_addc_u32 s3, s87, 0
	s_add_u32 s4, s86, 0x1100
	s_addc_u32 s5, s87, 0
	v_readlane_b32 s8, v253, 23
	s_waitcnt lgkmcnt(0)
	s_mul_i32 s16, s6, s8
	s_add_u32 s6, s86, 0x1200
	s_mul_i32 s16, s16, s7
	s_addc_u32 s7, s87, 0
	s_add_u32 s8, s86, 0x1300
	s_addc_u32 s9, s87, 0
	s_mov_b32 s17, 1
	v_mov_b32_e32 v17, 0
	s_branch .LBB0_1491

	.amdhsa_kernel _Z5k_fwd1P
		.amdhsa_group_segment_fixed_size 0
		.amdhsa_private_segment_fixed_size 0
		.amdhsa_kernarg_size 480
		.amdhsa_user_sgpr_count 2
		.amdhsa_user_sgpr_dispatch_ptr 0
		.amdhsa_user_sgpr_queue_ptr 0
		.amdhsa_user_sgpr_kernarg_segment_ptr 1
		.amdhsa_user_sgpr_dispatch_id 0
		.amdhsa_user_sgpr_kernarg_preload_length 0
		.amdhsa_user_sgpr_kernarg_preload_offset 0
		.amdhsa_user_sgpr_private_segment_size 0
		.amdhsa_uses_dynamic_stack 0
		.amdhsa_enable_private_segment 0
		.amdhsa_system_sgpr_workgroup_id_x 1
		.amdhsa_system_sgpr_workgroup_id_y 0
		.amdhsa_system_sgpr_workgroup_id_z 0
		.amdhsa_system_sgpr_workgroup_info 0
		.amdhsa_system_vgpr_workitem_id 0
		.amdhsa_next_free_vgpr 256
		.amdhsa_next_free_sgpr 102
		.amdhsa_accum_offset 256
		.amdhsa_reserve_vcc 1
		.amdhsa_float_round_mode_32 0
		.amdhsa_float_round_mode_16_64 0
		.amdhsa_float_denorm_mode_32 3
		.amdhsa_float_denorm_mode_16_64 3
		.amdhsa_dx10_clamp 1
		.amdhsa_ieee_mode 1
		.amdhsa_fp16_overflow 0
		.amdhsa_tg_split 0
		.amdhsa_exception_fp_ieee_invalid_op 0
		.amdhsa_exception_fp_denorm_src 0
		.amdhsa_exception_fp_ieee_div_zero 0
		.amdhsa_exception_fp_ieee_overflow 0
		.amdhsa_exception_fp_ieee_underflow 0
		.amdhsa_exception_fp_ieee_inexact 0
		.amdhsa_exception_int_div_zero 0
	.end_amdhsa_kernel

amdhsa.kernels:
  - .agpr_count:     0
    .args:
      - .offset:         0
        .size:           224
        .value_kind:     by_value
      - .offset:         224
        .size:           4
        .value_kind:     hidden_block_count_x
      - .offset:         228
        .size:           4
        .value_kind:     hidden_block_count_y
      - .offset:         232
        .size:           4
        .value_kind:     hidden_block_count_z
      - .offset:         236
        .size:           2
        .value_kind:     hidden_group_size_x
      - .offset:         238
        .size:           2
        .value_kind:     hidden_group_size_y
      - .offset:         240
        .size:           2
        .value_kind:     hidden_group_size_z
      - .offset:         242
        .size:           2
        .value_kind:     hidden_remainder_x
      - .offset:         244
        .size:           2
        .value_kind:     hidden_remainder_y
      - .offset:         246
        .size:           2
        .value_kind:     hidden_remainder_z
      - .offset:         264
        .size:           8
        .value_kind:     hidden_global_offset_x
      - .offset:         272
        .size:           8
        .value_kind:     hidden_global_offset_y
      - .offset:         280
        .size:           8
        .value_kind:     hidden_global_offset_z
      - .offset:         288
        .size:           2
        .value_kind:     hidden_grid_dims
      - .offset:         344
        .size:           4
        .value_kind:     hidden_dynamic_lds_size
    .group_segment_fixed_size: 0
    .kernarg_segment_align: 8
    .kernarg_segment_size: 480
    .language:       OpenCL C
    .language_version:
      - 2
      - 0
    .max_flat_workgroup_size: 512
    .name:           _Z5k_fwd1P
    .private_segment_fixed_size: 0
    .sgpr_count:     108
    .sgpr_spill_count: 172
    .symbol:         _Z5k_fwd1P.kd
    .uniform_work_group_size: 1
    .uses_dynamic_stack: false
    .vgpr_count:     256
    .vgpr_spill_count: 0
    .wavefront_size: 64
